# stack10 variant: P.V MFMAs issued k-slice-major (4 independent accumulators back to back)
# speedup vs baseline: 1.0234x; 1.0082x over previous
.Li0_kskip:
	ds_read_b64_tr_b16 v[180:181], v158 offset:0
	ds_read_b64_tr_b16 v[182:183], v158 offset:0x800
	ds_read_b64_tr_b16 v[184:185], v158 offset:0x200
	ds_read_b64_tr_b16 v[186:187], v158 offset:0xa00
	s_waitcnt lgkmcnt(5)
	v_mfma_f32_32x32x16_bf16 v[64:79], v[228:231], v[104:107], v[64:79]
	v_max_f32_e32 v194, v166, v166
	v_max_f32_e32 v195, v164, v164
	v_max_f32_e32 v194, v195, v194
	v_sub_f32_e32 v195, v194, v165
	v_mul_f32_e32 v195, 0x3db504f3, v195
	v_cmp_ge_f32_e32 vcc, s88, v195
	s_waitcnt lgkmcnt(4)
	v_mfma_f32_32x32x16_bf16 v[64:79], v[188:191], v[108:111], v[64:79]
	s_cmp_eq_u64 vcc, exec
	s_cbranch_scc0 .Li0_fb
	v_mov_b32_e32 v166, v165
	s_sub_i32 s52, s83, 64
	s_cmp_le_i32 s52, s25
	s_cbranch_scc1 .Li0_sm
	s_nop 7
	v_add_u32_e32 v112, 0x5b, v162
	v_cmp_gt_u32_e32 vcc, s86, v112
	v_add_u32_e32 v112, s83, v163
	v_add_u32_e32 v112, 0xffffffa1, v112
	v_cndmask_b32_e32 v64, v141, v64, vcc
	v_cmp_lt_u32_e32 vcc, s87, v112
	v_add_u32_e32 v112, 0x59, v162
	s_nop 0
	v_cndmask_b32_e32 v65, v141, v65, vcc
	v_cmp_gt_u32_e32 vcc, s86, v112
	v_add_u32_e32 v112, 0x58, v162
	s_nop 0
	v_cndmask_b32_e32 v66, v141, v66, vcc
	v_cmp_gt_u32_e32 vcc, s86, v112
	v_add_u32_e32 v112, 0x53, v162
	s_nop 0
	v_cndmask_b32_e32 v67, v141, v67, vcc
	v_cmp_gt_u32_e32 vcc, s86, v112
	v_add_u32_e32 v112, 0x52, v162
	s_nop 0
	v_cndmask_b32_e32 v68, v141, v68, vcc
	v_cmp_gt_u32_e32 vcc, s86, v112
	v_add_u32_e32 v112, 0x51, v162
	s_nop 0
	v_cndmask_b32_e32 v69, v141, v69, vcc
	v_cmp_gt_u32_e32 vcc, s86, v112
	v_add_u32_e32 v112, 0x50, v162
	s_nop 0
	v_cndmask_b32_e32 v70, v141, v70, vcc
	v_cmp_gt_u32_e32 vcc, s86, v112
	v_add_u32_e32 v112, 0x4b, v162
	s_nop 0
	v_cndmask_b32_e32 v71, v141, v71, vcc
	v_cmp_gt_u32_e32 vcc, s86, v112
	v_add_u32_e32 v112, 0x4a, v162
	s_nop 0
	v_cndmask_b32_e32 v72, v141, v72, vcc
	v_cmp_gt_u32_e32 vcc, s86, v112
	v_add_u32_e32 v112, 0x49, v162
	s_nop 0
	v_cndmask_b32_e32 v73, v141, v73, vcc
	v_cmp_gt_u32_e32 vcc, s86, v112
	v_add_u32_e32 v112, 0x48, v162
	s_nop 0
	v_cndmask_b32_e32 v74, v141, v74, vcc
	v_cmp_gt_u32_e32 vcc, s86, v112
	v_add_u32_e32 v112, 0x43, v162
	s_nop 0
	v_cndmask_b32_e32 v75, v141, v75, vcc
	v_cmp_gt_u32_e32 vcc, s86, v112
	v_add_u32_e32 v112, 0x42, v162
	s_nop 0
	v_cndmask_b32_e32 v76, v141, v76, vcc
	v_cmp_gt_u32_e32 vcc, s86, v112
	v_add_u32_e32 v112, 0x41, v162
	s_nop 0
	v_cndmask_b32_e32 v77, v141, v77, vcc
	v_cmp_gt_u32_e32 vcc, s86, v112
	v_add_u32_e32 v112, 64, v162
	s_nop 0
	v_cndmask_b32_e32 v78, v141, v78, vcc
	v_cmp_gt_u32_e32 vcc, s86, v112
	s_nop 1
	v_cndmask_b32_e32 v79, v141, v79, vcc
.Li0_sm:
	ds_read_b64_tr_b16 v[188:189], v158 offset:0x400
	ds_read_b64_tr_b16 v[190:191], v158 offset:0xc00
	ds_read_b64_tr_b16 v[192:193], v158 offset:0x600
	ds_read_b64_tr_b16 v[194:195], v158 offset:0xe00
	s_waitcnt lgkmcnt(4)
	v_mfma_f32_32x32x16_bf16 v[48:63], v[176:179], v[180:183], v[48:63]
	ds_read_b64_tr_b16 v[180:181], v158 offset:0x1000
	ds_read_b64_tr_b16 v[182:183], v158 offset:0x1800
	v_mul_f32_e32 v114, 0xbe0293ee, v166
	v_max_f32_e32 v112, v65, v65
	v_max_f32_e32 v113, v64, v64
	v_fmamk_f32 v64, v64, 0x3e0293ee, v114
	v_max_f32_e32 v112, v113, v112
	v_exp_f32_e32 v64, v64
	v_mfma_f32_32x32x16_bf16 v[32:47], v[176:179], v[184:187], v[32:47]
	ds_read_b64_tr_b16 v[184:185], v158 offset:0x1200
	ds_read_b64_tr_b16 v[186:187], v158 offset:0x1a00
	v_fmamk_f32 v65, v65, 0x3e0293ee, v114
	v_max3_f32 v112, v112, v66, v67
	v_exp_f32_e32 v65, v65
	v_fmamk_f32 v66, v66, 0x3e0293ee, v114
	v_exp_f32_e32 v66, v66
	v_fmamk_f32 v67, v67, 0x3e0293ee, v114
	s_waitcnt lgkmcnt(6)
	v_mfma_f32_32x32x16_bf16 v[16:31], v[176:179], v[188:191], v[16:31]
	ds_read_b64_tr_b16 v[188:189], v158 offset:0x1400
	ds_read_b64_tr_b16 v[190:191], v158 offset:0x1c00
	v_max3_f32 v112, v112, v68, v69
	v_exp_f32_e32 v67, v67
	v_fmamk_f32 v68, v68, 0x3e0293ee, v114
	v_add_f32_e32 v115, 0, v64
	v_exp_f32_e32 v68, v68
	v_fmamk_f32 v69, v69, 0x3e0293ee, v114
	s_waitcnt lgkmcnt(6)
	v_mfma_f32_32x32x16_bf16 v[0:15], v[176:179], v[192:195], v[0:15]
	ds_read_b64_tr_b16 v[192:193], v158 offset:0x1600
	ds_read_b64_tr_b16 v[194:195], v158 offset:0x1e00
	v_max3_f32 v112, v112, v70, v71
	v_add_f32_e32 v115, v65, v115
	v_exp_f32_e32 v69, v69
	v_fmamk_f32 v70, v70, 0x3e0293ee, v114
	v_add_f32_e32 v115, v66, v115
	v_exp_f32_e32 v70, v70
	s_waitcnt lgkmcnt(0)
	v_mfma_f32_32x32x16_bf16 v[48:63], v[124:127], v[180:183], v[48:63]
	ds_read_b64_tr_b16 v[180:181], v158 offset:0x2000
	ds_read_b64_tr_b16 v[182:183], v158 offset:0x2800
	v_fmamk_f32 v71, v71, 0x3e0293ee, v114
	v_max3_f32 v112, v112, v72, v73
	v_add_f32_e32 v115, v67, v115
	v_exp_f32_e32 v71, v71
	v_fmamk_f32 v72, v72, 0x3e0293ee, v114
	v_add_f32_e32 v115, v68, v115
	v_mfma_f32_32x32x16_bf16 v[32:47], v[124:127], v[184:187], v[32:47]
	ds_read_b64_tr_b16 v[184:185], v158 offset:0x2200
	ds_read_b64_tr_b16 v[186:187], v158 offset:0x2a00
	v_exp_f32_e32 v72, v72
	v_fmamk_f32 v73, v73, 0x3e0293ee, v114
	v_max3_f32 v112, v112, v74, v75
	v_add_f32_e32 v115, v69, v115
	v_exp_f32_e32 v73, v73
	v_fmamk_f32 v74, v74, 0x3e0293ee, v114
	v_mfma_f32_32x32x16_bf16 v[16:31], v[124:127], v[188:191], v[16:31]
	ds_read_b64_tr_b16 v[188:189], v158 offset:0x2400
	ds_read_b64_tr_b16 v[190:191], v158 offset:0x2c00
	v_add_f32_e32 v115, v70, v115
	v_exp_f32_e32 v74, v74
	v_fmamk_f32 v75, v75, 0x3e0293ee, v114
	v_max3_f32 v112, v112, v76, v77
	v_add_f32_e32 v115, v71, v115
	v_exp_f32_e32 v75, v75
	v_mfma_f32_32x32x16_bf16 v[0:15], v[124:127], v[192:195], v[0:15]
	ds_read_b64_tr_b16 v[192:193], v158 offset:0x2600
	ds_read_b64_tr_b16 v[194:195], v158 offset:0x2e00
	v_fmamk_f32 v76, v76, 0x3e0293ee, v114
	v_add_f32_e32 v115, v72, v115
	v_exp_f32_e32 v76, v76
	v_fmamk_f32 v77, v77, 0x3e0293ee, v114
	v_max3_f32 v112, v112, v78, v79
	v_add_f32_e32 v115, v73, v115
	s_waitcnt lgkmcnt(0)
	v_mfma_f32_32x32x16_bf16 v[48:63], v[172:175], v[180:183], v[48:63]
	ds_read_b64_tr_b16 v[180:181], v158 offset:0x3000
	ds_read_b64_tr_b16 v[182:183], v158 offset:0x3800
	v_exp_f32_e32 v77, v77
	v_fmamk_f32 v78, v78, 0x3e0293ee, v114
	v_add_f32_e32 v115, v74, v115
	v_exp_f32_e32 v78, v78
	v_fmac_f32_e32 v114, 0x3e0293ee, v79
	v_add_f32_e32 v115, v75, v115
	v_mfma_f32_32x32x16_bf16 v[32:47], v[172:175], v[184:187], v[32:47]
	ds_read_b64_tr_b16 v[184:185], v158 offset:0x3200
	ds_read_b64_tr_b16 v[186:187], v158 offset:0x3a00
	v_exp_f32_e32 v79, v114
	v_add_f32_e32 v114, v76, v115
	v_mov_b32_e32 v113, v112
	v_add_f32_e32 v114, v77, v114
	s_nop 0
	v_permlane32_swap_b32_e32 v112, v113
	v_add_f32_e32 v114, v78, v114
	v_mfma_f32_32x32x16_bf16 v[16:31], v[172:175], v[188:191], v[16:31]
	ds_read_b64_tr_b16 v[188:189], v158 offset:0x3400
	ds_read_b64_tr_b16 v[190:191], v158 offset:0x3c00
	v_add_f32_e32 v120, v79, v114
	v_max_f32_e32 v113, v113, v113
	v_max_f32_e32 v112, v112, v112
	v_max_f32_e32 v164, v112, v113
	v_mov_b32_e32 v121, v120
	v_cvt_pk_bf16_f32 v112, v64, v65
	v_mfma_f32_32x32x16_bf16 v[0:15], v[172:175], v[192:195], v[0:15]
	ds_read_b64_tr_b16 v[192:193], v158 offset:0x3600
	ds_read_b64_tr_b16 v[194:195], v158 offset:0x3e00
	v_cvt_pk_bf16_f32 v113, v66, v67
	v_cvt_pk_bf16_f32 v114, v68, v69
	v_cvt_pk_bf16_f32 v115, v70, v71
	v_cvt_pk_bf16_f32 v116, v72, v73
	v_cvt_pk_bf16_f32 v117, v74, v75
	v_cvt_pk_bf16_f32 v118, v76, v77
	s_waitcnt lgkmcnt(0)
	v_mfma_f32_32x32x16_bf16 v[48:63], v[168:171], v[180:183], v[48:63]
	v_cvt_pk_bf16_f32 v119, v78, v79
	s_nop 1
	v_permlane32_swap_b32_e32 v120, v121
	v_permlane32_swap_b32_e32 v112, v114
	v_permlane32_swap_b32_e32 v113, v115
	v_permlane32_swap_b32_e32 v116, v118
	v_permlane32_swap_b32_e32 v117, v119
	v_mfma_f32_32x32x16_bf16 v[32:47], v[168:171], v[184:187], v[32:47]
	ds_write_b128 v157, v[112:115] offset:4096
	ds_write_b128 v157, v[116:119] offset:5120
	v_add_f32_e32 v120, v120, v121
	v_add_f32_e32 v155, v155, v120
	v_mfma_f32_32x32x16_bf16 v[16:31], v[168:171], v[188:191], v[16:31]
	v_mfma_f32_32x32x16_bf16 v[0:15], v[168:171], v[192:195], v[0:15]
	s_and_saveexec_b64 s[52:53], s[4:5]
	ds_write_b32 v160, v164 offset:8448
	s_or_b64 exec, exec, s[52:53]
	s_waitcnt vmcnt(0)
	s_waitcnt vmcnt(0) lgkmcnt(0)
	s_barrier
	s_branch .LBB0_748

.Li1_kskip:
	ds_read_b64_tr_b16 v[180:181], v158 offset:0x8000
	ds_read_b64_tr_b16 v[182:183], v158 offset:0x8800
	ds_read_b64_tr_b16 v[184:185], v158 offset:0x8200
	ds_read_b64_tr_b16 v[186:187], v158 offset:0x8a00
	s_waitcnt lgkmcnt(5)
	v_mfma_f32_32x32x16_bf16 v[64:79], v[228:231], v[104:107], v[64:79]
	v_max_f32_e32 v194, v128, v128
	v_max_f32_e32 v195, v164, v164
	v_max_f32_e32 v194, v195, v194
	v_sub_f32_e32 v195, v194, v166
	v_mul_f32_e32 v195, 0x3db504f3, v195
	v_cmp_ge_f32_e32 vcc, s88, v195
	s_waitcnt lgkmcnt(4)
	v_mfma_f32_32x32x16_bf16 v[64:79], v[188:191], v[108:111], v[64:79]
	s_cmp_eq_u64 vcc, exec
	s_cbranch_scc0 .Li1_fb
	v_mov_b32_e32 v165, v166
	s_cmp_le_i32 s83, s25
	s_cbranch_scc1 .Li1_sm
	s_nop 7
	v_add_u32_e32 v112, 27, v162
	v_cmp_gt_u32_e32 vcc, s86, v112
	v_add_u32_e32 v112, s83, v163
	v_subrev_u32_e32 v112, 31, v112
	v_cndmask_b32_e32 v64, v141, v64, vcc
	v_cmp_lt_u32_e32 vcc, s87, v112
	v_add_u32_e32 v112, 25, v162
	s_nop 0
	v_cndmask_b32_e32 v65, v141, v65, vcc
	v_cmp_gt_u32_e32 vcc, s86, v112
	v_add_u32_e32 v112, 24, v162
	s_nop 0
	v_cndmask_b32_e32 v66, v141, v66, vcc
	v_cmp_gt_u32_e32 vcc, s86, v112
	v_add_u32_e32 v112, 19, v162
	s_nop 0
	v_cndmask_b32_e32 v67, v141, v67, vcc
	v_cmp_gt_u32_e32 vcc, s86, v112
	v_add_u32_e32 v112, 18, v162
	s_nop 0
	v_cndmask_b32_e32 v68, v141, v68, vcc
	v_cmp_gt_u32_e32 vcc, s86, v112
	v_add_u32_e32 v112, 17, v162
	s_nop 0
	v_cndmask_b32_e32 v69, v141, v69, vcc
	v_cmp_gt_u32_e32 vcc, s86, v112
	v_add_u32_e32 v112, 16, v162
	s_nop 0
	v_cndmask_b32_e32 v70, v141, v70, vcc
	v_cmp_gt_u32_e32 vcc, s86, v112
	v_add_u32_e32 v112, 11, v162
	s_nop 0
	v_cndmask_b32_e32 v71, v141, v71, vcc
	v_cmp_gt_u32_e32 vcc, s86, v112
	v_add_u32_e32 v112, 10, v162
	s_nop 0
	v_cndmask_b32_e32 v72, v141, v72, vcc
	v_cmp_gt_u32_e32 vcc, s86, v112
	v_add_u32_e32 v112, 9, v162
	s_nop 0
	v_cndmask_b32_e32 v73, v141, v73, vcc
	v_cmp_gt_u32_e32 vcc, s86, v112
	v_add_u32_e32 v112, 8, v162
	s_nop 0
	v_cndmask_b32_e32 v74, v141, v74, vcc
	v_cmp_gt_u32_e32 vcc, s86, v112
	v_add_u32_e32 v112, 3, v162
	s_nop 0
	v_cndmask_b32_e32 v75, v141, v75, vcc
	v_cmp_gt_u32_e32 vcc, s86, v112
	v_add_u32_e32 v112, 2, v162
	s_nop 0
	v_cndmask_b32_e32 v76, v141, v76, vcc
	v_cmp_gt_u32_e32 vcc, s86, v112
	v_add_u32_e32 v112, 1, v162
	s_nop 0
	v_cndmask_b32_e32 v77, v141, v77, vcc
	v_cmp_gt_u32_e32 vcc, s86, v112
	s_nop 1
	v_cndmask_b32_e32 v78, v141, v78, vcc
	v_cmp_gt_u32_e32 vcc, s86, v162
	s_nop 1
	v_cndmask_b32_e32 v79, v141, v79, vcc
.Li1_sm:
	ds_read_b64_tr_b16 v[188:189], v158 offset:0x8400
	ds_read_b64_tr_b16 v[190:191], v158 offset:0x8c00
	ds_read_b64_tr_b16 v[192:193], v158 offset:0x8600
	ds_read_b64_tr_b16 v[194:195], v158 offset:0x8e00
	s_waitcnt lgkmcnt(4)
	v_mfma_f32_32x32x16_bf16 v[48:63], v[176:179], v[180:183], v[48:63]
	ds_read_b64_tr_b16 v[180:181], v158 offset:0x9000
	ds_read_b64_tr_b16 v[182:183], v158 offset:0x9800
	v_mul_f32_e32 v114, 0xbe0293ee, v165
	v_max_f32_e32 v112, v65, v65
	v_max_f32_e32 v113, v64, v64
	v_fmamk_f32 v64, v64, 0x3e0293ee, v114
	v_max_f32_e32 v112, v113, v112
	v_exp_f32_e32 v64, v64
	v_mfma_f32_32x32x16_bf16 v[32:47], v[176:179], v[184:187], v[32:47]
	ds_read_b64_tr_b16 v[184:185], v158 offset:0x9200
	ds_read_b64_tr_b16 v[186:187], v158 offset:0x9a00
	v_fmamk_f32 v65, v65, 0x3e0293ee, v114
	v_max3_f32 v112, v112, v66, v67
	v_exp_f32_e32 v65, v65
	v_fmamk_f32 v66, v66, 0x3e0293ee, v114
	v_exp_f32_e32 v66, v66
	v_fmamk_f32 v67, v67, 0x3e0293ee, v114
	s_waitcnt lgkmcnt(6)
	v_mfma_f32_32x32x16_bf16 v[16:31], v[176:179], v[188:191], v[16:31]
	ds_read_b64_tr_b16 v[188:189], v158 offset:0x9400
	ds_read_b64_tr_b16 v[190:191], v158 offset:0x9c00
	v_max3_f32 v112, v112, v68, v69
	v_exp_f32_e32 v67, v67
	v_fmamk_f32 v68, v68, 0x3e0293ee, v114
	v_add_f32_e32 v115, 0, v64
	v_exp_f32_e32 v68, v68
	v_fmamk_f32 v69, v69, 0x3e0293ee, v114
	s_waitcnt lgkmcnt(6)
	v_mfma_f32_32x32x16_bf16 v[0:15], v[176:179], v[192:195], v[0:15]
	ds_read_b64_tr_b16 v[192:193], v158 offset:0x9600
	ds_read_b64_tr_b16 v[194:195], v158 offset:0x9e00
	v_max3_f32 v112, v112, v70, v71
	v_add_f32_e32 v115, v65, v115
	v_exp_f32_e32 v69, v69
	v_fmamk_f32 v70, v70, 0x3e0293ee, v114
	v_add_f32_e32 v115, v66, v115
	v_exp_f32_e32 v70, v70
	s_waitcnt lgkmcnt(0)
	v_mfma_f32_32x32x16_bf16 v[48:63], v[168:171], v[180:183], v[48:63]
	ds_read_b64_tr_b16 v[180:181], v158 offset:0xa000
	ds_read_b64_tr_b16 v[182:183], v158 offset:0xa800
	v_fmamk_f32 v71, v71, 0x3e0293ee, v114
	v_max3_f32 v112, v112, v72, v73
	v_add_f32_e32 v115, v67, v115
	v_exp_f32_e32 v71, v71
	v_fmamk_f32 v72, v72, 0x3e0293ee, v114
	v_add_f32_e32 v115, v68, v115
	v_mfma_f32_32x32x16_bf16 v[32:47], v[168:171], v[184:187], v[32:47]
	ds_read_b64_tr_b16 v[184:185], v158 offset:0xa200
	ds_read_b64_tr_b16 v[186:187], v158 offset:0xaa00
	v_exp_f32_e32 v72, v72
	v_fmamk_f32 v73, v73, 0x3e0293ee, v114
	v_max3_f32 v112, v112, v74, v75
	v_add_f32_e32 v115, v69, v115
	v_exp_f32_e32 v73, v73
	v_fmamk_f32 v74, v74, 0x3e0293ee, v114
	v_mfma_f32_32x32x16_bf16 v[16:31], v[168:171], v[188:191], v[16:31]
	ds_read_b64_tr_b16 v[188:189], v158 offset:0xa400
	ds_read_b64_tr_b16 v[190:191], v158 offset:0xac00
	v_add_f32_e32 v115, v70, v115
	v_exp_f32_e32 v74, v74
	v_fmamk_f32 v75, v75, 0x3e0293ee, v114
	v_max3_f32 v112, v112, v76, v77
	v_add_f32_e32 v115, v71, v115
	v_exp_f32_e32 v75, v75
	v_mfma_f32_32x32x16_bf16 v[0:15], v[168:171], v[192:195], v[0:15]
	ds_read_b64_tr_b16 v[192:193], v158 offset:0xa600
	ds_read_b64_tr_b16 v[194:195], v158 offset:0xae00
	v_fmamk_f32 v76, v76, 0x3e0293ee, v114
	v_add_f32_e32 v115, v72, v115
	v_exp_f32_e32 v76, v76
	v_fmamk_f32 v77, v77, 0x3e0293ee, v114
	v_max3_f32 v112, v112, v78, v79
	v_add_f32_e32 v115, v73, v115
	s_waitcnt lgkmcnt(0)
	v_mfma_f32_32x32x16_bf16 v[48:63], v[172:175], v[180:183], v[48:63]
	ds_read_b64_tr_b16 v[180:181], v158 offset:0xb000
	ds_read_b64_tr_b16 v[182:183], v158 offset:0xb800
	v_exp_f32_e32 v77, v77
	v_fmamk_f32 v78, v78, 0x3e0293ee, v114
	v_add_f32_e32 v115, v74, v115
	v_exp_f32_e32 v78, v78
	v_fmac_f32_e32 v114, 0x3e0293ee, v79
	v_add_f32_e32 v115, v75, v115
	v_mfma_f32_32x32x16_bf16 v[32:47], v[172:175], v[184:187], v[32:47]
	ds_read_b64_tr_b16 v[184:185], v158 offset:0xb200
	ds_read_b64_tr_b16 v[186:187], v158 offset:0xba00
	v_exp_f32_e32 v79, v114
	v_add_f32_e32 v114, v76, v115
	v_mov_b32_e32 v113, v112
	v_add_f32_e32 v114, v77, v114
	s_nop 0
	v_permlane32_swap_b32_e32 v112, v113
	v_add_f32_e32 v114, v78, v114
	v_mfma_f32_32x32x16_bf16 v[16:31], v[172:175], v[188:191], v[16:31]
	ds_read_b64_tr_b16 v[188:189], v158 offset:0xb400
	ds_read_b64_tr_b16 v[190:191], v158 offset:0xbc00
	v_add_f32_e32 v120, v79, v114
	v_max_f32_e32 v113, v113, v113
	v_max_f32_e32 v112, v112, v112
	v_max_f32_e32 v164, v112, v113
	v_mov_b32_e32 v121, v120
	v_cvt_pk_bf16_f32 v112, v64, v65
	v_mfma_f32_32x32x16_bf16 v[0:15], v[172:175], v[192:195], v[0:15]
	ds_read_b64_tr_b16 v[192:193], v158 offset:0xb600
	ds_read_b64_tr_b16 v[194:195], v158 offset:0xbe00
	v_cvt_pk_bf16_f32 v113, v66, v67
	v_cvt_pk_bf16_f32 v114, v68, v69
	v_cvt_pk_bf16_f32 v115, v70, v71
	v_cvt_pk_bf16_f32 v116, v72, v73
	v_cvt_pk_bf16_f32 v117, v74, v75
	v_cvt_pk_bf16_f32 v118, v76, v77
	s_waitcnt lgkmcnt(0)
	v_mfma_f32_32x32x16_bf16 v[48:63], v[124:127], v[180:183], v[48:63]
	v_cvt_pk_bf16_f32 v119, v78, v79
	s_nop 1
	v_permlane32_swap_b32_e32 v120, v121
	v_permlane32_swap_b32_e32 v112, v114
	v_permlane32_swap_b32_e32 v113, v115
	v_permlane32_swap_b32_e32 v116, v118
	v_permlane32_swap_b32_e32 v117, v119
	v_mfma_f32_32x32x16_bf16 v[32:47], v[124:127], v[184:187], v[32:47]
	ds_write_b128 v157, v[112:115]
	ds_write_b128 v157, v[116:119] offset:1024
	v_add_f32_e32 v120, v120, v121
	v_add_f32_e32 v155, v155, v120
	v_mfma_f32_32x32x16_bf16 v[16:31], v[124:127], v[188:191], v[16:31]
	v_mfma_f32_32x32x16_bf16 v[0:15], v[124:127], v[192:195], v[0:15]
	s_and_saveexec_b64 s[54:55], s[4:5]
	ds_write_b32 v160, v164 offset:8192
	s_or_b64 exec, exec, s[54:55]
	s_waitcnt vmcnt(0)
	s_waitcnt vmcnt(0) lgkmcnt(0)
	s_barrier
	s_branch .LBB0_733
